# speedup vs baseline: 1.0002x; 1.0002x over previous
; __device__ __forceinline__ void phase_attn(const Params& p, char* smraw) {
;     ...
;   for (int i = 0; i < 64; ++i) { gq = fmaxf(gq, fabsf(p.qgain[i])); gk = fmaxf(gk, fabsf(p.kgain[i])); }
.LBB0_255:
	global_load_dwordx4 v[4:7], v3, s[46:47] offset:16
	global_load_dwordx4 v[8:11], v3, s[46:47]
	global_load_dwordx4 v[12:15], v3, s[48:49]
	global_load_dwordx4 v[16:19], v3, s[48:49] offset:16
	global_load_dwordx4 v[20:23], v3, s[46:47] offset:48
	global_load_dwordx4 v[24:27], v3, s[46:47] offset:32
	global_load_dwordx4 v[28:31], v3, s[48:49] offset:32
	global_load_dwordx4 v[32:35], v3, s[48:49] offset:48
	global_load_dwordx4 v[36:39], v3, s[46:47] offset:80
	global_load_dwordx4 v[40:43], v3, s[46:47] offset:64
	global_load_dwordx4 v[44:47], v3, s[48:49] offset:64
	global_load_dwordx4 v[48:51], v3, s[48:49] offset:80
	global_load_dwordx4 v[52:55], v3, s[46:47] offset:112
	global_load_dwordx4 v[56:59], v3, s[46:47] offset:96
	global_load_dwordx4 v[60:63], v3, s[48:49] offset:96
	global_load_dwordx4 v[64:67], v3, s[48:49] offset:112
	global_load_dwordx4 v[68:71], v3, s[46:47] offset:144
	global_load_dwordx4 v[72:75], v3, s[46:47] offset:128
	global_load_dwordx4 v[76:79], v3, s[48:49] offset:128
	global_load_dwordx4 v[80:83], v3, s[48:49] offset:144
	global_load_dwordx4 v[84:87], v3, s[46:47] offset:176
	global_load_dwordx4 v[88:91], v3, s[46:47] offset:160
	global_load_dwordx4 v[92:95], v3, s[48:49] offset:160
	global_load_dwordx4 v[96:99], v3, s[48:49] offset:176
	global_load_dwordx4 v[100:103], v3, s[46:47] offset:208
	global_load_dwordx4 v[104:107], v3, s[46:47] offset:192
	global_load_dwordx4 v[108:111], v3, s[48:49] offset:192
	global_load_dwordx4 v[112:115], v3, s[48:49] offset:208
	global_load_dwordx4 v[116:119], v3, s[46:47] offset:240
	global_load_dwordx4 v[120:123], v3, s[46:47] offset:224
	global_load_dwordx4 v[124:127], v3, s[48:49] offset:224
	global_load_dwordx4 v[128:131], v3, s[48:49] offset:240
	s_waitcnt vmcnt(0)
	v_max3_f32 v1, v1, |v4|, |v5|
	v_max3_f32 v1, v1, |v6|, |v7|
	v_max3_f32 v1, v1, |v8|, |v9|
	v_max3_f32 v1, v1, |v10|, |v11|
	v_max3_f32 v2, v2, |v12|, |v13|
	v_max3_f32 v2, v2, |v14|, |v15|
	v_max3_f32 v2, v2, |v16|, |v17|
	v_max3_f32 v2, v2, |v18|, |v19|
	v_max3_f32 v1, v1, |v20|, |v21|
	v_max3_f32 v1, v1, |v22|, |v23|
	v_max3_f32 v1, v1, |v24|, |v25|
	v_max3_f32 v1, v1, |v26|, |v27|
	v_max3_f32 v2, v2, |v28|, |v29|
	v_max3_f32 v2, v2, |v30|, |v31|
	v_max3_f32 v2, v2, |v32|, |v33|
	v_max3_f32 v2, v2, |v34|, |v35|
	v_max3_f32 v1, v1, |v36|, |v37|
	v_max3_f32 v1, v1, |v38|, |v39|
	v_max3_f32 v1, v1, |v40|, |v41|
	v_max3_f32 v1, v1, |v42|, |v43|
	v_max3_f32 v2, v2, |v44|, |v45|
	v_max3_f32 v2, v2, |v46|, |v47|
	v_max3_f32 v2, v2, |v48|, |v49|
	v_max3_f32 v2, v2, |v50|, |v51|
	v_max3_f32 v1, v1, |v52|, |v53|
	v_max3_f32 v1, v1, |v54|, |v55|
	v_max3_f32 v1, v1, |v56|, |v57|
	v_max3_f32 v1, v1, |v58|, |v59|
	v_max3_f32 v2, v2, |v60|, |v61|
	v_max3_f32 v2, v2, |v62|, |v63|
	v_max3_f32 v2, v2, |v64|, |v65|
	v_max3_f32 v2, v2, |v66|, |v67|
	v_max3_f32 v1, v1, |v68|, |v69|
	v_max3_f32 v1, v1, |v70|, |v71|
	v_max3_f32 v1, v1, |v72|, |v73|
	v_max3_f32 v1, v1, |v74|, |v75|
	v_max3_f32 v2, v2, |v76|, |v77|
	v_max3_f32 v2, v2, |v78|, |v79|
	v_max3_f32 v2, v2, |v80|, |v81|
	v_max3_f32 v2, v2, |v82|, |v83|
	v_max3_f32 v1, v1, |v84|, |v85|
	v_max3_f32 v1, v1, |v86|, |v87|
	v_max3_f32 v1, v1, |v88|, |v89|
	v_max3_f32 v1, v1, |v90|, |v91|
	v_max3_f32 v2, v2, |v92|, |v93|
	v_max3_f32 v2, v2, |v94|, |v95|
	v_max3_f32 v2, v2, |v96|, |v97|
	v_max3_f32 v2, v2, |v98|, |v99|
	v_max3_f32 v1, v1, |v100|, |v101|
	v_max3_f32 v1, v1, |v102|, |v103|
	v_max3_f32 v1, v1, |v104|, |v105|
	v_max3_f32 v1, v1, |v106|, |v107|
	v_max3_f32 v2, v2, |v108|, |v109|
	v_max3_f32 v2, v2, |v110|, |v111|
	v_max3_f32 v2, v2, |v112|, |v113|
	v_max3_f32 v2, v2, |v114|, |v115|
	v_max3_f32 v1, v1, |v116|, |v117|
	v_max3_f32 v1, v1, |v118|, |v119|
	v_max3_f32 v1, v1, |v120|, |v121|
	v_max3_f32 v1, v1, |v122|, |v123|
	v_max3_f32 v2, v2, |v124|, |v125|
	v_max3_f32 v2, v2, |v126|, |v127|
	v_max3_f32 v2, v2, |v128|, |v129|
	v_max3_f32 v2, v2, |v130|, |v131|
	s_cmpk_lt_i32 s2, 0x1040
	s_cbranch_scc0 .LBB0_281
; __device__ __forceinline__ void phase_attn(const Params& p, char* smraw) {
;     ...
;   const float thresh = 11.5416f * gq * gk + 32.f;
;   bf16x8 tri[2];
; #pragma unroll
;   for (int kk = 0; kk < 2; ++kk)
; #pragma unroll
;     for (int j = 0; j < 8; ++j) {
;       int jj = 16 * kk + 8 * (j >> 2) + 4 * hf + (j & 3);
;       tri[kk][j] = (jj >= lc) ? (short)0x3F80 : (short)0;
;     }
;   for (int item = blockIdx.x; item < 64 * 65; item += gridDim.x) {
;     const int bh = item & 63, qt = item >> 6;
;     const int qbase = qt * 128 + w * 32, qpos = qbase + lc;
;     const u16* qptr = p.qbuf + ((size_t)bh * LP + qpos) * 64;
;     bf16x8 qf[4];
; #pragma unroll
;     for (int ks = 0; ks < 4; ++ks) qf[ks] = *(const bf16x8*)(qptr + ks * 16 + hf * 8);
;     f32x16 o[2];
; #pragma unroll
;     for (int r = 0; r < 16; ++r) { o[0][r] = 0.f; o[1][r] = 0.f; }
;     float carry = 0.f; int done = 0;
;     const u16* kbase = p.kbuf + (size_t)bh * LP * 64;
;     const u16* vbase = p.vT + (size_t)bh * 64 * LP;
;     const int kt_hi = 2 * qt + 1;
;     u32x4 rk[2], rv[2];
;     auto gload = [&](int kt) {
;       const int key0 = kt * 64;
; #pragma unroll
;       for (int cc = 0; cc < 2; ++cc) {
;         const int c = tid + cc * 256, row = c >> 3, ch = c & 7;
;         rk[cc] = *(const u32x4*)(kbase + (size_t)(key0 + row) * 64 + ch * 8);
;         rv[cc] = *(const u32x4*)(vbase + (size_t)row * LP + key0 + ch * 8);
;       }
	v_bfe_u32 v4, v0, 5, 1
	v_mul_f32_e32 v1, 0x4138aa65, v1
	v_lshlrev_b32_e32 v104, 2, v4
	v_and_b32_e32 v105, 31, v0
	v_fmaak_f32 v124, v2, v1, 0x42000000
	v_or_b32_e32 v2, 16, v104
	v_mov_b32_e32 v5, 0x3f80
	v_cmp_lt_u32_e32 vcc, v2, v105
	v_or_b32_e32 v7, 17, v104
	v_or_b32_e32 v2, 18, v104
	v_cndmask_b32_e64 v6, v5, 0, vcc
	v_cmp_lt_u32_e32 vcc, v7, v105
	v_or_b32_e32 v9, 19, v104
	v_or_b32_e32 v11, 25, v104
	v_cndmask_b32_e64 v7, v5, 0, vcc
	v_cmp_lt_u32_e32 vcc, v2, v105
	v_or_b32_e32 v2, 24, v104
	v_or_b32_e32 v15, 1, v104
	v_cndmask_b32_e64 v8, v5, 0, vcc
	v_cmp_lt_u32_e32 vcc, v9, v105
	v_or_b32_e32 v17, 3, v104
	v_or_b32_e32 v19, 9, v104
	v_cndmask_b32_e64 v9, v5, 0, vcc
	v_cmp_lt_u32_e32 vcc, v2, v105
	v_or_b32_e32 v2, 26, v104
	v_and_b32_e32 v3, 63, v0
	v_cndmask_b32_e64 v10, v5, 0, vcc
	v_cmp_lt_u32_e32 vcc, v2, v105
	v_or_b32_e32 v2, 27, v104
	v_ashrrev_i32_e32 v1, 6, v0
	v_cndmask_b32_e64 v12, v5, 0, vcc
	v_cmp_lt_u32_e32 vcc, v11, v105
	v_ashrrev_i32_e32 v126, 3, v0
	s_movk_i32 s4, 0x4100
	v_cndmask_b32_e64 v11, v5, 0, vcc
	v_cmp_lt_u32_e32 vcc, v2, v105
	v_or_b32_e32 v2, 2, v104
	v_mad_i64_i32 v[108:109], s[0:1], v126, s4, 0
	v_cndmask_b32_e64 v13, v5, 0, vcc
	v_cmp_lt_u32_e32 vcc, v104, v105
	v_mov_b32_e32 v107, 0
	v_lshlrev_b32_e32 v125, 5, v1
	v_cndmask_b32_e64 v14, v5, 0, vcc
	v_cmp_lt_u32_e32 vcc, v15, v105
	v_lshlrev_b32_e32 v128, 2, v1
	v_or_b32_e32 v1, 32, v105
	v_cndmask_b32_e64 v15, v5, 0, vcc
	v_cmp_lt_u32_e32 vcc, v2, v105
	v_or_b32_e32 v2, 8, v104
	v_readlane_b32 s8, v254, 0
	v_cndmask_b32_e64 v16, v5, 0, vcc
	v_cmp_lt_u32_e32 vcc, v17, v105
	v_lshlrev_b32_e32 v21, 3, v4
	v_readlane_b32 s20, v254, 12
	v_cndmask_b32_e64 v17, v5, 0, vcc
	v_cmp_lt_u32_e32 vcc, v2, v105
	v_or_b32_e32 v2, 10, v104
	v_readlane_b32 s21, v254, 13
	v_cndmask_b32_e64 v18, v5, 0, vcc
	v_cmp_lt_u32_e32 vcc, v2, v105
	v_or_b32_e32 v2, 11, v104
	v_mbcnt_hi_u32_b32 v134, -1, v191
	v_cndmask_b32_e64 v20, v5, 0, vcc
	v_cmp_lt_u32_e32 vcc, v19, v105
	s_mov_b32 s42, s92
	s_mov_b32 s67, 0
	v_cndmask_b32_e64 v19, v5, 0, vcc
	v_cmp_lt_u32_e32 vcc, v2, v105
	v_lshlrev_b32_e32 v2, 3, v0
	v_add_u32_e32 v0, 0x100, v0
	v_ashrrev_i32_e32 v127, 3, v0
	v_mad_i64_i32 v[110:111], s[0:1], v127, s4, 0
	s_movk_i32 s0, 0x90
	v_cndmask_b32_e64 v5, v5, 0, vcc
	v_cmp_eq_u32_e64 s[4:5], 0, v3
	v_mul_lo_u32 v3, v126, s0
	v_mul_lo_u32 v23, v127, s0
	s_mov_b32 s0, 0x5040100
	v_lshlrev_b32_e32 v0, 4, v4
	v_perm_b32 v67, v5, v20, s0
	v_mul_u32_u24_e32 v5, 0x90, v1
	v_mov_b32_e32 v1, v107
	v_and_b32_e32 v2, 56, v2
	v_sub_u32_e32 v4, v0, v21
	s_movk_i32 s1, 0x88
	v_perm_b32 v68, v7, v6, s0
	v_mul_u32_u24_e32 v6, 0x88, v105
	v_lshl_add_u64 v[112:113], s[20:21], 0, v[0:1]
	v_and_or_b32 v1, v134, 64, v105
	v_lshlrev_b32_e32 v22, 1, v2
	v_mul_lo_u32 v21, v126, s1
	v_mul_lo_u32 v24, v127, s1
	v_perm_b32 v66, v19, v18, s0
	v_perm_b32 v65, v17, v16, s0
	v_perm_b32 v64, v15, v14, s0
	v_perm_b32 v70, v11, v10, s0
	v_perm_b32 v69, v9, v8, s0
	v_perm_b32 v71, v13, v12, s0
	v_mul_u32_u24_e32 v7, 0x90, v105
	s_movk_i32 s0, 0x2400
	v_lshlrev_b32_e32 v135, 2, v1
	v_add_u32_e32 v1, v4, v6
	v_lshlrev_b32_e32 v106, 1, v2
	v_add_u32_e32 v129, v22, v3
	v_add3_u32 v130, v22, v21, s0
	v_add_u32_e32 v131, v22, v23
	v_add3_u32 v132, v22, v24, s0
	v_add_u32_e32 v133, v0, v5
	s_movk_i32 s78, 0x6f
	v_add_u32_e32 v136, v0, v7
	v_lshlrev_b32_e32 v114, 1, v104
	v_add_u32_e32 v137, 0x2000, v1
	v_add_u32_e32 v138, 0x3000, v1
	v_mov_b32_e32 v139, 0x7149f2ca
	s_mov_b32 s79, s2
	v_readlane_b32 s9, v254, 1
	v_readlane_b32 s10, v254, 2
	v_readlane_b32 s11, v254, 3
	v_readlane_b32 s12, v254, 4
	v_readlane_b32 s13, v254, 5
	v_readlane_b32 s14, v254, 6
	v_readlane_b32 s15, v254, 7
	v_readlane_b32 s16, v254, 8
	v_readlane_b32 s17, v254, 9
	v_readlane_b32 s18, v254, 10
	v_readlane_b32 s19, v254, 11
	v_readlane_b32 s22, v254, 14
	v_readlane_b32 s23, v254, 15
	s_branch .LBB0_259
